# g3 + sliding-window epilogue gate fragments prefetched into the dead rope/gain registers after the last head's Q preparation
# baseline (speedup 1.0000x reference)
.Lswa_gpf:
	v_bfe_u32 v90, v0, 4, 2
	v_mov_b32_e32 v91, 0
	v_lshlrev_b32_e32 v90, 3, v90
	v_lshl_add_u64 v[90:91], v[82:83], 0, v[90:91]
	global_load_dwordx2 v[224:225], v[90:91], off offset:3072
	global_load_dwordx2 v[226:227], v[90:91], off offset:3104
	global_load_dwordx2 v[228:229], v[90:91], off offset:3136
	global_load_dwordx2 v[230:231], v[90:91], off offset:3168
	global_load_dwordx2 v[232:233], v[90:91], off offset:3200
	global_load_dwordx2 v[234:235], v[90:91], off offset:3232
	global_load_dwordx2 v[236:237], v[90:91], off offset:3264
	global_load_dwordx2 v[238:239], v[90:91], off offset:3296
	global_load_dwordx2 v[248:249], v[90:91], off offset:3328
	global_load_dwordx2 v[250:251], v[90:91], off offset:3360
	global_load_dwordx2 v[252:253], v[90:91], off offset:3392
	global_load_dwordx2 v[254:255], v[90:91], off offset:3424
	global_load_dwordx2 v[240:241], v[90:91], off offset:3456
	global_load_dwordx2 v[246:247], v[90:91], off offset:3488
	s_branch .LBB0_189
.LBB0_208:
	s_waitcnt vmcnt(0)
	v_lshlrev_b32_e32 v2, 1, v111
	v_lshl_add_u64 v[14:15], v[82:83], 0, v[2:3]
	v_mov_b64_e32 v[20:21], v[224:225]
	v_readlane_b32 s8, v244, 0
	v_lshlrev_b32_e32 v18, 2, v111
	v_readlane_b32 s12, v244, 4
	v_readlane_b32 s13, v244, 5
	v_mov_b32_e32 v16, v110
	s_nop 1
	v_permlane16_swap_b32 v16, v110
	v_readlane_b32 s4, v244, 57
	v_lshlrev_b64 v[12:13], 11, v[80:81]
	v_readlane_b32 s6, v244, 59
	v_readlane_b32 s7, v244, 60
	global_load_dwordx4 v[8:11], v18, s[12:13] offset:2048
	v_mov_b64_e32 v[46:47], v[226:227]
	v_mov_b64_e32 v[52:53], v[228:229]
	v_mov_b64_e32 v[54:55], v[230:231]
	global_load_dwordx4 v[56:59], v18, s[12:13] offset:2112
	global_load_dwordx4 v[60:63], v18, s[12:13] offset:2176
	global_load_dwordx4 v[64:67], v18, s[12:13] offset:2240
	v_mov_b64_e32 v[68:69], v[232:233]
	global_load_dwordx4 v[70:73], v18, s[12:13] offset:2304
	v_mov_b64_e32 v[74:75], v[234:235]
	v_mov_b64_e32 v[76:77], v[236:237]
	v_mov_b64_e32 v[78:79], v[238:239]
	global_load_dwordx4 v[84:87], v18, s[12:13] offset:2368
	global_load_dwordx4 v[88:91], v18, s[12:13] offset:2432
	global_load_dwordx4 v[92:95], v18, s[12:13] offset:2496
	v_mov_b64_e32 v[96:97], v[248:249]
	global_load_dwordx4 v[98:101], v18, s[12:13] offset:2560
	v_mov_b64_e32 v[102:103], v[250:251]
	v_mov_b64_e32 v[104:105], v[252:253]
	v_mov_b64_e32 v[106:107], v[254:255]
	global_load_dwordx4 v[116:119], v18, s[12:13] offset:2624
	global_load_dwordx4 v[120:123], v18, s[12:13] offset:2688
	global_load_dwordx4 v[124:127], v18, s[12:13] offset:2752
	v_mov_b64_e32 v[132:133], v[240:241]
	global_load_dwordx4 v[134:137], v18, s[12:13] offset:2816
	v_mov_b64_e32 v[138:139], v[246:247]
	global_load_dwordx2 v[140:141], v[14:15], off offset:3520
	global_load_dwordx2 v[142:143], v[14:15], off offset:3552
	global_load_dwordx4 v[144:147], v18, s[12:13] offset:2880
	global_load_dwordx4 v[148:151], v18, s[12:13] offset:2944
	global_load_dwordx4 v[152:155], v18, s[12:13] offset:3008
	v_readlane_b32 s32, v244, 2
	v_readlane_b32 s33, v244, 3
	v_readlane_b32 s24, v243, 8
	v_readlane_b32 s26, v244, 50
	v_readlane_b32 s27, v244, 51
	v_readlane_b32 s28, v243, 30
	v_readlane_b32 s30, v243, 5
	v_readlane_b32 s31, v243, 6
	v_lshrrev_b32_e32 v108, 1, v0
	v_and_b32_e32 v129, 1, v0
	v_and_b32_e32 v168, 15, v0
	v_lshrrev_b32_e32 v169, 6, v0
	v_lshl_add_u32 v108, s24, 8, v108
	v_lshlrev_b32_e32 v129, 6, v129
	v_or_b32_e32 v168, s28, v168
	v_lshl_add_u32 v108, v108, 10, v129
	v_lshl_add_u32 v168, v169, 4, v168
	v_bfe_u32 v169, v0, 4, 2
	v_mul_u32_u24_e32 v168, 0x1200, v168
	v_lshl_add_u32 v168, v169, 4, v168
	global_load_dwordx4 v[156:159], v108, s[26:27] offset:48
	global_load_dwordx4 v[160:163], v108, s[26:27] offset:32
	global_load_dwordx4 v[164:167], v108, s[26:27] offset:16
	global_load_dwordx4 v[172:175], v108, s[26:27]
	global_load_dwordx4 v[176:179], v108, s[26:27] offset:512
	global_load_dwordx4 v[196:199], v108, s[26:27] offset:528
	global_load_dwordx4 v[200:203], v108, s[26:27] offset:544
	global_load_dwordx4 v[204:207], v108, s[26:27] offset:560
	global_load_dwordx4 v[208:211], v168, s[30:31] offset:3584
	global_load_dwordx4 v[212:215], v168, s[30:31] offset:3648
	v_and_b32_e32 v195, 63, v0
	v_lshlrev_b32_e32 v195, 2, v195
	global_load_dword v195, v195, s[32:33]
	s_waitcnt lgkmcnt(0)
	v_add_f32_e32 v19, v110, v16
	v_mov_b32_e32 v28, v19
	s_nop 1
	v_permlane32_swap_b32 v28, v19
	s_mov_b64 s[0:1], 0xdde0400
	v_lshl_add_u64 v[12:13], s[6:7], 0, v[12:13]
	v_lshl_add_u64 v[12:13], v[12:13], 0, s[0:1]
	s_mov_b32 s0, 0x800000
	s_waitcnt lgkmcnt(0)
	v_add_f32_e32 v19, v19, v28
	v_fmamk_f32 v19, v19, 0x3b800000, v180
	v_mul_f32_e32 v28, 0x4b800000, v19
	v_cmp_gt_f32_e32 vcc, s0, v19
	ds_read2_b64 v[4:7], v109 offset1:4
	v_cndmask_b32_e32 v19, v19, v28, vcc
	v_rsq_f32_e32 v19, v19
	v_lshl_add_u64 v[26:27], v[12:13], 0, v[2:3]
	s_waitcnt lgkmcnt(0)
	v_lshlrev_b32_e32 v29, 16, v4
	v_and_b32_e32 v31, 0xffff0000, v4
	v_mul_f32_e32 v4, 0x45800000, v19
	v_lshlrev_b32_e32 v33, 16, v5
	v_and_b32_e32 v35, 0xffff0000, v5
	v_cndmask_b32_e32 v5, v19, v4, vcc
	v_mov_b32_e32 v38, v5
	v_mov_b32_e32 v40, v5
	v_mov_b32_e32 v42, v5
	v_readlane_b32 s88, v243, 5
	v_readlane_b32 s20, v243, 30
	v_readlane_b32 s89, v243, 6
	v_readlane_b32 s0, v243, 8
	v_mov_b32_e32 v45, v3
	v_mov_b32_e32 v115, v3
	v_readlane_b32 s2, v244, 62
	v_readlane_b32 s10, v244, 2
	v_readlane_b32 s11, v244, 3
	v_mov_b32_e32 v51, v3
	v_readlane_b32 s9, v244, 1
	v_readlane_b32 s3, v244, 63
	v_readlane_b32 s14, v244, 6
	v_readlane_b32 s15, v244, 7
	v_readlane_b32 s5, v244, 58
	v_readlane_b32 s86, v243, 3
	v_readlane_b32 s22, v243, 28
	v_mov_b32_e32 v130, 0
	s_mov_b64 s[4:5], 0
	v_readlane_b32 s58, v243, 2
	v_readlane_b32 s87, v243, 4
	s_movk_i32 s84, 0x7f
	v_readlane_b32 s23, v243, 29
	v_readlane_b32 s21, v243, 31
	v_lshlrev_b32_e32 v28, 16, v20
	v_mul_f32_e32 v4, 0xbfb8aa3b, v28
	v_exp_f32_e32 v4, v4
	v_and_b32_e32 v30, 0xffff0000, v20
	v_mul_f32_e32 v19, 0xbfb8aa3b, v30
	v_exp_f32_e32 v19, v19
	v_add_f32_e32 v4, 1.0, v4
	v_rcp_f32_e32 v4, v4
	v_lshlrev_b32_e32 v32, 16, v21
	v_and_b32_e32 v34, 0xffff0000, v21
	v_mul_f32_e32 v20, 0xbfb8aa3b, v32
	v_mul_f32_e32 v21, 0xbfb8aa3b, v34
	v_exp_f32_e32 v36, v20
	v_add_f32_e32 v19, 1.0, v19
	v_exp_f32_e32 v37, v21
	v_pk_mul_f32 v[20:21], v[4:5], v[28:29]
	v_rcp_f32_e32 v4, v19
	v_add_f32_e32 v19, 1.0, v36
	s_waitcnt vmcnt(28)
	v_mul_f32_e32 v8, v8, v21
	v_add_f32_e32 v36, 1.0, v37
	v_pk_mul_f32 v[28:29], v[4:5], v[30:31]
	v_rcp_f32_e32 v4, v19
	v_mul_f32_e32 v19, v20, v8
	v_mul_f32_e32 v8, v9, v29
	v_mul_f32_e32 v20, v28, v8
	v_pk_mul_f32 v[8:9], v[4:5], v[32:33]
	v_rcp_f32_e32 v4, v36
	v_mul_f32_e32 v9, v10, v9
	v_mul_f32_e32 v10, v8, v9
	v_cvt_pk_bf16_f32 v20, v19, v20
	v_pk_mul_f32 v[8:9], v[4:5], v[34:35]
	v_lshlrev_b32_e32 v28, 16, v7
	v_mul_f32_e32 v4, v11, v9
	v_mul_f32_e32 v4, v8, v4
	v_cvt_pk_bf16_f32 v21, v10, v4
	global_store_dwordx2 v[26:27], v[20:21], off
	v_and_b32_e32 v30, 0xffff0000, v7
	v_lshlrev_b32_e32 v27, 16, v46
	v_and_b32_e32 v7, 0xffff0000, v46
	v_lshlrev_b32_e32 v29, 16, v47
	v_and_b32_e32 v31, 0xffff0000, v47
	v_mul_f32_e32 v4, 0xbfb8aa3b, v27
	v_mul_f32_e32 v19, 0xbfb8aa3b, v7
	v_mul_f32_e32 v22, 0xbfb8aa3b, v29
	v_mul_f32_e32 v23, 0xbfb8aa3b, v31
	v_exp_f32_e32 v4, v4
	v_exp_f32_e32 v19, v19
	v_exp_f32_e32 v22, v22
	v_exp_f32_e32 v23, v23
	v_add_f32_e32 v4, 1.0, v4
	v_add_f32_e32 v19, 1.0, v19
	v_add_f32_e32 v22, 1.0, v22
	v_add_f32_e32 v23, 1.0, v23
	v_rcp_f32_e32 v33, v4
	v_rcp_f32_e32 v35, v19
	v_rcp_f32_e32 v37, v22
	v_rcp_f32_e32 v39, v23
	v_lshlrev_b32_e32 v26, 16, v6
	v_and_b32_e32 v6, 0xffff0000, v6
	v_mov_b32_e32 v32, v5
	v_mov_b32_e32 v34, v5
	v_mov_b32_e32 v36, v5
	v_pk_mul_f32 v[22:23], v[32:33], v[26:27]
	v_pk_mul_f32 v[6:7], v[34:35], v[6:7]
	v_pk_mul_f32 v[26:27], v[36:37], v[28:29]
	v_mov_b32_e32 v21, v3
	v_or_b32_e32 v20, 32, v2
	v_pk_mul_f32 v[28:29], v[38:39], v[30:31]
	v_lshl_add_u64 v[20:21], v[12:13], 0, v[20:21]
	v_and_b32_e32 v31, 0xffff0000, v53
	s_waitcnt vmcnt(28)
	v_mul_f32_e32 v4, v56, v22
	v_mul_f32_e32 v6, v57, v6
	v_mul_f32_e32 v8, v58, v26
	v_mul_f32_e32 v9, v59, v28
	v_mul_f32_e32 v6, v6, v7
	v_mul_f32_e32 v7, v8, v27
	v_mul_f32_e32 v4, v4, v23
	v_mul_f32_e32 v8, v9, v29
	v_cvt_pk_bf16_f32 v6, v4, v6
	v_cvt_pk_bf16_f32 v7, v7, v8
	global_store_dwordx2 v[20:21], v[6:7], off
	ds_read2_b64 v[20:23], v109 offset0:8 offset1:12
	v_lshlrev_b32_e32 v27, 16, v52
	v_lshlrev_b32_e32 v29, 16, v53
	v_mul_f32_e32 v4, 0xbfb8aa3b, v27
	v_mul_f32_e32 v25, 0xbfb8aa3b, v31
	s_waitcnt lgkmcnt(0)
	v_lshlrev_b32_e32 v28, 16, v21
	v_and_b32_e32 v30, 0xffff0000, v21
	v_and_b32_e32 v21, 0xffff0000, v52
	v_mul_f32_e32 v19, 0xbfb8aa3b, v21
	v_mul_f32_e32 v24, 0xbfb8aa3b, v29
	v_exp_f32_e32 v4, v4
	v_exp_f32_e32 v19, v19
	v_exp_f32_e32 v24, v24
	v_exp_f32_e32 v25, v25
	v_add_f32_e32 v4, 1.0, v4
	v_add_f32_e32 v19, 1.0, v19
	v_add_f32_e32 v24, 1.0, v24
	v_add_f32_e32 v25, 1.0, v25
	v_rcp_f32_e32 v33, v4
	v_rcp_f32_e32 v35, v19
	v_rcp_f32_e32 v37, v24
	v_rcp_f32_e32 v39, v25
	v_lshlrev_b32_e32 v26, 16, v20
	v_and_b32_e32 v20, 0xffff0000, v20
	v_pk_mul_f32 v[24:25], v[32:33], v[26:27]
	v_pk_mul_f32 v[20:21], v[34:35], v[20:21]
	v_pk_mul_f32 v[26:27], v[36:37], v[28:29]
	v_mov_b32_e32 v11, v3
	v_or_b32_e32 v10, 64, v2
	v_pk_mul_f32 v[28:29], v[38:39], v[30:31]
	v_lshl_add_u64 v[10:11], v[12:13], 0, v[10:11]
	v_mov_b32_e32 v30, v5
	s_waitcnt vmcnt(28)
	v_mul_f32_e32 v4, v60, v24
	v_mul_f32_e32 v6, v61, v20
	v_mul_f32_e32 v7, v62, v26
	v_mul_f32_e32 v8, v63, v28
	v_mul_f32_e32 v6, v6, v21
	v_mul_f32_e32 v7, v7, v27
	v_mul_f32_e32 v4, v4, v25
	v_mul_f32_e32 v8, v8, v29
	v_cvt_pk_bf16_f32 v6, v4, v6
	v_cvt_pk_bf16_f32 v7, v7, v8
	global_store_dwordx2 v[10:11], v[6:7], off
	v_lshlrev_b32_e32 v26, 16, v23
	v_and_b32_e32 v28, 0xffff0000, v23
	v_lshlrev_b32_e32 v21, 16, v54
	v_and_b32_e32 v23, 0xffff0000, v54
	v_lshlrev_b32_e32 v27, 16, v55
	v_and_b32_e32 v29, 0xffff0000, v55
	v_mul_f32_e32 v4, 0xbfb8aa3b, v21
	v_mul_f32_e32 v16, 0xbfb8aa3b, v23
	v_mul_f32_e32 v17, 0xbfb8aa3b, v27
	v_mul_f32_e32 v19, 0xbfb8aa3b, v29
	v_exp_f32_e32 v4, v4
	v_exp_f32_e32 v16, v16
	v_exp_f32_e32 v17, v17
	v_exp_f32_e32 v19, v19
	v_add_f32_e32 v4, 1.0, v4
	v_add_f32_e32 v16, 1.0, v16
	v_add_f32_e32 v17, 1.0, v17
	v_add_f32_e32 v19, 1.0, v19
	v_rcp_f32_e32 v31, v4
	v_rcp_f32_e32 v33, v16
	v_rcp_f32_e32 v35, v17
	v_rcp_f32_e32 v37, v19
	v_lshlrev_b32_e32 v20, 16, v22
	v_and_b32_e32 v22, 0xffff0000, v22
	v_pk_mul_f32 v[16:17], v[30:31], v[20:21]
	v_pk_mul_f32 v[20:21], v[32:33], v[22:23]
	v_pk_mul_f32 v[22:23], v[34:35], v[26:27]
	v_mov_b32_e32 v11, v3
	v_or_b32_e32 v10, 0x60, v2
	v_pk_mul_f32 v[26:27], v[36:37], v[28:29]
	v_lshl_add_u64 v[10:11], v[12:13], 0, v[10:11]
	s_waitcnt vmcnt(28)
	v_mul_f32_e32 v4, v64, v16
	v_mul_f32_e32 v6, v65, v20
	v_mul_f32_e32 v7, v66, v22
	v_mul_f32_e32 v8, v67, v26
	v_mul_f32_e32 v6, v6, v21
	v_mul_f32_e32 v7, v7, v23
	v_mul_f32_e32 v4, v4, v17
	v_mul_f32_e32 v8, v8, v27
	v_cvt_pk_bf16_f32 v6, v4, v6
	v_cvt_pk_bf16_f32 v7, v7, v8
	global_store_dwordx2 v[10:11], v[6:7], off
	ds_read2_b64 v[20:23], v109 offset0:16 offset1:20
	v_lshlrev_b32_e32 v31, 16, v68
	v_lshlrev_b32_e32 v33, 16, v69
	v_and_b32_e32 v35, 0xffff0000, v69
	s_waitcnt lgkmcnt(0)
	v_lshlrev_b32_e32 v32, 16, v21
	v_and_b32_e32 v34, 0xffff0000, v21
	v_and_b32_e32 v21, 0xffff0000, v68
	v_mul_f32_e32 v4, 0xbfb8aa3b, v31
	v_mul_f32_e32 v19, 0xbfb8aa3b, v21
	v_mul_f32_e32 v24, 0xbfb8aa3b, v33
	v_mul_f32_e32 v25, 0xbfb8aa3b, v35
	v_exp_f32_e32 v4, v4
	v_exp_f32_e32 v19, v19
	v_exp_f32_e32 v24, v24
	v_exp_f32_e32 v25, v25
	v_add_f32_e32 v4, 1.0, v4
	v_add_f32_e32 v19, 1.0, v19
	v_add_f32_e32 v24, 1.0, v24
	v_add_f32_e32 v25, 1.0, v25
	v_rcp_f32_e32 v37, v4
	v_rcp_f32_e32 v39, v19
	v_rcp_f32_e32 v41, v24
	v_rcp_f32_e32 v43, v25
	v_lshlrev_b32_e32 v30, 16, v20
	v_and_b32_e32 v20, 0xffff0000, v20
	v_pk_mul_f32 v[24:25], v[36:37], v[30:31]
	v_pk_mul_f32 v[20:21], v[38:39], v[20:21]
	v_pk_mul_f32 v[30:31], v[40:41], v[32:33]
	v_mov_b32_e32 v17, v3
	v_or_b32_e32 v16, 0x80, v2
	v_pk_mul_f32 v[32:33], v[42:43], v[34:35]
	v_lshl_add_u64 v[16:17], v[12:13], 0, v[16:17]
	v_mov_b32_e32 v34, v5
	s_waitcnt vmcnt(28)
	v_mul_f32_e32 v4, v70, v24
	v_mul_f32_e32 v8, v71, v20
	v_mul_f32_e32 v9, v72, v30
	v_mul_f32_e32 v10, v73, v32
	v_mul_f32_e32 v8, v8, v21
	v_mul_f32_e32 v9, v9, v31
	v_mul_f32_e32 v4, v4, v25
	v_mul_f32_e32 v10, v10, v33
	v_cvt_pk_bf16_f32 v8, v4, v8
	v_cvt_pk_bf16_f32 v9, v9, v10
	global_store_dwordx2 v[16:17], v[8:9], off
	v_lshlrev_b32_e32 v24, 16, v23
	v_and_b32_e32 v30, 0xffff0000, v23
	v_lshlrev_b32_e32 v21, 16, v74
	v_and_b32_e32 v23, 0xffff0000, v74
	v_lshlrev_b32_e32 v25, 16, v75
	v_and_b32_e32 v31, 0xffff0000, v75
	v_mul_f32_e32 v4, 0xbfb8aa3b, v21
	v_mul_f32_e32 v19, 0xbfb8aa3b, v23
	v_mul_f32_e32 v26, 0xbfb8aa3b, v25
	v_mul_f32_e32 v27, 0xbfb8aa3b, v31
	v_exp_f32_e32 v4, v4
	v_exp_f32_e32 v19, v19
	v_exp_f32_e32 v26, v26
	v_exp_f32_e32 v27, v27
	v_add_f32_e32 v4, 1.0, v4
	v_add_f32_e32 v19, 1.0, v19
	v_add_f32_e32 v26, 1.0, v26
	v_add_f32_e32 v27, 1.0, v27
	v_rcp_f32_e32 v33, v4
	v_rcp_f32_e32 v35, v19
	v_rcp_f32_e32 v37, v26
	v_rcp_f32_e32 v39, v27
	v_lshlrev_b32_e32 v20, 16, v22
	v_and_b32_e32 v22, 0xffff0000, v22
	v_mov_b32_e32 v32, v5
	v_pk_mul_f32 v[20:21], v[32:33], v[20:21]
	v_pk_mul_f32 v[22:23], v[34:35], v[22:23]
	v_pk_mul_f32 v[24:25], v[36:37], v[24:25]
	v_mov_b32_e32 v17, v3
	v_or_b32_e32 v16, 0xa0, v2
	v_pk_mul_f32 v[26:27], v[38:39], v[30:31]
	v_lshl_add_u64 v[16:17], v[12:13], 0, v[16:17]
	v_and_b32_e32 v31, 0xffff0000, v77
	s_waitcnt vmcnt(28)
	v_mul_f32_e32 v4, v84, v20
	v_mul_f32_e32 v8, v85, v22
	v_mul_f32_e32 v9, v86, v24
	v_mul_f32_e32 v10, v87, v26
	v_mul_f32_e32 v8, v8, v23
	v_mul_f32_e32 v9, v9, v25
	v_mul_f32_e32 v4, v4, v21
	v_mul_f32_e32 v10, v10, v27
	v_cvt_pk_bf16_f32 v8, v4, v8
	v_cvt_pk_bf16_f32 v9, v9, v10
	global_store_dwordx2 v[16:17], v[8:9], off
	ds_read2_b64 v[20:23], v109 offset0:24 offset1:28
	v_lshlrev_b32_e32 v25, 16, v76
	v_lshlrev_b32_e32 v27, 16, v77
	v_mul_f32_e32 v4, 0xbfb8aa3b, v25
	v_mul_f32_e32 v29, 0xbfb8aa3b, v31
	s_waitcnt lgkmcnt(0)
	v_lshlrev_b32_e32 v26, 16, v21
	v_and_b32_e32 v30, 0xffff0000, v21
	v_and_b32_e32 v21, 0xffff0000, v76
	v_mul_f32_e32 v19, 0xbfb8aa3b, v21
	v_mul_f32_e32 v28, 0xbfb8aa3b, v27
	v_exp_f32_e32 v4, v4
	v_exp_f32_e32 v19, v19
	v_exp_f32_e32 v28, v28
	v_exp_f32_e32 v29, v29
	v_add_f32_e32 v4, 1.0, v4
	v_add_f32_e32 v19, 1.0, v19
	v_add_f32_e32 v28, 1.0, v28
	v_add_f32_e32 v29, 1.0, v29
	v_rcp_f32_e32 v33, v4
	v_rcp_f32_e32 v35, v19
	v_rcp_f32_e32 v37, v28
	v_rcp_f32_e32 v39, v29
	v_lshlrev_b32_e32 v24, 16, v20
	v_and_b32_e32 v20, 0xffff0000, v20
	v_pk_mul_f32 v[24:25], v[32:33], v[24:25]
	v_pk_mul_f32 v[20:21], v[34:35], v[20:21]
	v_pk_mul_f32 v[26:27], v[36:37], v[26:27]
	v_mov_b32_e32 v17, v3
	v_or_b32_e32 v16, 0xc0, v2
	v_pk_mul_f32 v[28:29], v[38:39], v[30:31]
	v_lshl_add_u64 v[16:17], v[12:13], 0, v[16:17]
	v_mov_b32_e32 v30, v5
	s_waitcnt vmcnt(28)
	v_mul_f32_e32 v4, v88, v24
	v_mul_f32_e32 v8, v89, v20
	v_mul_f32_e32 v9, v90, v26
	v_mul_f32_e32 v10, v91, v28
	v_mul_f32_e32 v8, v8, v21
	v_mul_f32_e32 v9, v9, v27
	v_mul_f32_e32 v4, v4, v25
	v_mul_f32_e32 v10, v10, v29
	v_cvt_pk_bf16_f32 v8, v4, v8
	v_cvt_pk_bf16_f32 v9, v9, v10
	global_store_dwordx2 v[16:17], v[8:9], off
	v_lshlrev_b32_e32 v26, 16, v23
	v_and_b32_e32 v28, 0xffff0000, v23
	v_lshlrev_b32_e32 v21, 16, v78
	v_and_b32_e32 v23, 0xffff0000, v78
	v_lshlrev_b32_e32 v27, 16, v79
	v_and_b32_e32 v29, 0xffff0000, v79
	v_mul_f32_e32 v4, 0xbfb8aa3b, v21
	v_mul_f32_e32 v6, 0xbfb8aa3b, v23
	v_mul_f32_e32 v7, 0xbfb8aa3b, v27
	v_mul_f32_e32 v19, 0xbfb8aa3b, v29
	v_exp_f32_e32 v4, v4
	v_exp_f32_e32 v6, v6
	v_exp_f32_e32 v7, v7
	v_exp_f32_e32 v19, v19
	v_add_f32_e32 v4, 1.0, v4
	v_add_f32_e32 v6, 1.0, v6
	v_add_f32_e32 v7, 1.0, v7
	v_add_f32_e32 v19, 1.0, v19
	v_rcp_f32_e32 v31, v4
	v_rcp_f32_e32 v33, v6
	v_rcp_f32_e32 v35, v7
	v_rcp_f32_e32 v37, v19
	v_lshlrev_b32_e32 v20, 16, v22
	v_and_b32_e32 v22, 0xffff0000, v22
	v_pk_mul_f32 v[6:7], v[30:31], v[20:21]
	v_pk_mul_f32 v[20:21], v[32:33], v[22:23]
	v_pk_mul_f32 v[22:23], v[34:35], v[26:27]
	v_mov_b32_e32 v17, v3
	v_or_b32_e32 v16, 0xe0, v2
	v_pk_mul_f32 v[26:27], v[36:37], v[28:29]
	v_lshl_add_u64 v[16:17], v[12:13], 0, v[16:17]
	s_waitcnt vmcnt(28)
	v_mul_f32_e32 v4, v92, v6
	v_mul_f32_e32 v6, v93, v20
	v_mul_f32_e32 v8, v94, v22
	v_mul_f32_e32 v9, v95, v26
	v_mul_f32_e32 v4, v4, v7
	v_mul_f32_e32 v6, v6, v21
	v_mul_f32_e32 v7, v8, v23
	v_mul_f32_e32 v8, v9, v27
	v_cvt_pk_bf16_f32 v6, v4, v6
	v_cvt_pk_bf16_f32 v7, v7, v8
	global_store_dwordx2 v[16:17], v[6:7], off
	ds_read2_b64 v[20:23], v109 offset0:32 offset1:36
	v_lshlrev_b32_e32 v31, 16, v96
	v_lshlrev_b32_e32 v33, 16, v97
	v_and_b32_e32 v35, 0xffff0000, v97
	s_waitcnt lgkmcnt(0)
	v_lshlrev_b32_e32 v32, 16, v21
	v_and_b32_e32 v34, 0xffff0000, v21
	v_and_b32_e32 v21, 0xffff0000, v96
	v_mul_f32_e32 v4, 0xbfb8aa3b, v31
	v_mul_f32_e32 v19, 0xbfb8aa3b, v21
	v_mul_f32_e32 v24, 0xbfb8aa3b, v33
	v_mul_f32_e32 v25, 0xbfb8aa3b, v35
	v_exp_f32_e32 v4, v4
	v_exp_f32_e32 v19, v19
	v_exp_f32_e32 v24, v24
	v_exp_f32_e32 v25, v25
	v_add_f32_e32 v4, 1.0, v4
	v_add_f32_e32 v19, 1.0, v19
	v_add_f32_e32 v24, 1.0, v24
	v_add_f32_e32 v25, 1.0, v25
	v_rcp_f32_e32 v37, v4
	v_rcp_f32_e32 v39, v19
	v_rcp_f32_e32 v41, v24
	v_rcp_f32_e32 v43, v25
	v_lshlrev_b32_e32 v30, 16, v20
	v_and_b32_e32 v20, 0xffff0000, v20
	v_pk_mul_f32 v[24:25], v[36:37], v[30:31]
	v_pk_mul_f32 v[20:21], v[38:39], v[20:21]
	v_pk_mul_f32 v[30:31], v[40:41], v[32:33]
	v_mov_b32_e32 v17, v3
	v_or_b32_e32 v16, 0x100, v2
	v_pk_mul_f32 v[32:33], v[42:43], v[34:35]
	v_lshl_add_u64 v[16:17], v[12:13], 0, v[16:17]
	v_mov_b32_e32 v34, v5
	s_waitcnt vmcnt(28)
	v_mul_f32_e32 v4, v98, v24
	v_mul_f32_e32 v8, v99, v20
	v_mul_f32_e32 v9, v100, v30
	v_mul_f32_e32 v10, v101, v32
	v_mul_f32_e32 v8, v8, v21
	v_mul_f32_e32 v9, v9, v31
	v_mul_f32_e32 v4, v4, v25
	v_mul_f32_e32 v10, v10, v33
	v_cvt_pk_bf16_f32 v8, v4, v8
	v_cvt_pk_bf16_f32 v9, v9, v10
	global_store_dwordx2 v[16:17], v[8:9], off
	v_lshlrev_b32_e32 v24, 16, v23
	v_and_b32_e32 v30, 0xffff0000, v23
	v_lshlrev_b32_e32 v21, 16, v102
	v_and_b32_e32 v23, 0xffff0000, v102
	v_lshlrev_b32_e32 v25, 16, v103
	v_and_b32_e32 v31, 0xffff0000, v103
	v_mul_f32_e32 v4, 0xbfb8aa3b, v21
	v_mul_f32_e32 v19, 0xbfb8aa3b, v23
	v_mul_f32_e32 v26, 0xbfb8aa3b, v25
	v_mul_f32_e32 v27, 0xbfb8aa3b, v31
	v_exp_f32_e32 v4, v4
	v_exp_f32_e32 v19, v19
	v_exp_f32_e32 v26, v26
	v_exp_f32_e32 v27, v27
	v_add_f32_e32 v4, 1.0, v4
	v_add_f32_e32 v19, 1.0, v19
	v_add_f32_e32 v26, 1.0, v26
	v_add_f32_e32 v27, 1.0, v27
	v_rcp_f32_e32 v33, v4
	v_rcp_f32_e32 v35, v19
	v_rcp_f32_e32 v37, v26
	v_rcp_f32_e32 v39, v27
	v_lshlrev_b32_e32 v20, 16, v22
	v_and_b32_e32 v22, 0xffff0000, v22
	v_mov_b32_e32 v32, v5
	v_pk_mul_f32 v[20:21], v[32:33], v[20:21]
	v_pk_mul_f32 v[22:23], v[34:35], v[22:23]
	v_pk_mul_f32 v[24:25], v[36:37], v[24:25]
	v_mov_b32_e32 v17, v3
	v_or_b32_e32 v16, 0x120, v2
	v_pk_mul_f32 v[26:27], v[38:39], v[30:31]
	v_lshl_add_u64 v[16:17], v[12:13], 0, v[16:17]
	v_and_b32_e32 v31, 0xffff0000, v105
	s_waitcnt vmcnt(28)
	v_mul_f32_e32 v4, v116, v20
	v_mul_f32_e32 v8, v117, v22
	v_mul_f32_e32 v9, v118, v24
	v_mul_f32_e32 v10, v119, v26
	v_mul_f32_e32 v8, v8, v23
	v_mul_f32_e32 v9, v9, v25
	v_mul_f32_e32 v4, v4, v21
	v_mul_f32_e32 v10, v10, v27
	v_cvt_pk_bf16_f32 v8, v4, v8
	v_cvt_pk_bf16_f32 v9, v9, v10
	global_store_dwordx2 v[16:17], v[8:9], off
	ds_read2_b64 v[20:23], v109 offset0:40 offset1:44
	v_lshlrev_b32_e32 v25, 16, v104
	v_lshlrev_b32_e32 v27, 16, v105
	v_mul_f32_e32 v4, 0xbfb8aa3b, v25
	v_mul_f32_e32 v29, 0xbfb8aa3b, v31
	s_waitcnt lgkmcnt(0)
	v_lshlrev_b32_e32 v26, 16, v21
	v_and_b32_e32 v30, 0xffff0000, v21
	v_and_b32_e32 v21, 0xffff0000, v104
	v_mul_f32_e32 v19, 0xbfb8aa3b, v21
	v_mul_f32_e32 v28, 0xbfb8aa3b, v27
	v_exp_f32_e32 v4, v4
	v_exp_f32_e32 v19, v19
	v_exp_f32_e32 v28, v28
	v_exp_f32_e32 v29, v29
	v_add_f32_e32 v4, 1.0, v4
	v_add_f32_e32 v19, 1.0, v19
	v_add_f32_e32 v28, 1.0, v28
	v_add_f32_e32 v29, 1.0, v29
	v_rcp_f32_e32 v33, v4
	v_rcp_f32_e32 v35, v19
	v_rcp_f32_e32 v37, v28
	v_rcp_f32_e32 v39, v29
	v_lshlrev_b32_e32 v24, 16, v20
	v_and_b32_e32 v20, 0xffff0000, v20
	v_pk_mul_f32 v[24:25], v[32:33], v[24:25]
	v_pk_mul_f32 v[20:21], v[34:35], v[20:21]
	v_pk_mul_f32 v[26:27], v[36:37], v[26:27]
	v_mov_b32_e32 v17, v3
	v_or_b32_e32 v16, 0x140, v2
	v_pk_mul_f32 v[28:29], v[38:39], v[30:31]
	v_lshl_add_u64 v[16:17], v[12:13], 0, v[16:17]
	v_mov_b32_e32 v30, v5
	s_waitcnt vmcnt(28)
	v_mul_f32_e32 v4, v120, v24
	v_mul_f32_e32 v8, v121, v20
	v_mul_f32_e32 v9, v122, v26
	v_mul_f32_e32 v10, v123, v28
	v_mul_f32_e32 v8, v8, v21
	v_mul_f32_e32 v9, v9, v27
	v_mul_f32_e32 v4, v4, v25
	v_mul_f32_e32 v10, v10, v29
	v_cvt_pk_bf16_f32 v8, v4, v8
	v_cvt_pk_bf16_f32 v9, v9, v10
	global_store_dwordx2 v[16:17], v[8:9], off
	v_lshlrev_b32_e32 v26, 16, v23
	v_and_b32_e32 v28, 0xffff0000, v23
	v_lshlrev_b32_e32 v21, 16, v106
	v_and_b32_e32 v23, 0xffff0000, v106
	v_lshlrev_b32_e32 v27, 16, v107
	v_and_b32_e32 v29, 0xffff0000, v107
	v_mul_f32_e32 v4, 0xbfb8aa3b, v21
	v_mul_f32_e32 v6, 0xbfb8aa3b, v23
	v_mul_f32_e32 v7, 0xbfb8aa3b, v27
	v_mul_f32_e32 v19, 0xbfb8aa3b, v29
	v_exp_f32_e32 v4, v4
	v_exp_f32_e32 v6, v6
	v_exp_f32_e32 v7, v7
	v_exp_f32_e32 v19, v19
	v_add_f32_e32 v4, 1.0, v4
	v_add_f32_e32 v6, 1.0, v6
	v_add_f32_e32 v7, 1.0, v7
	v_add_f32_e32 v19, 1.0, v19
	v_rcp_f32_e32 v31, v4
	v_rcp_f32_e32 v33, v6
	v_rcp_f32_e32 v35, v7
	v_rcp_f32_e32 v37, v19
	v_lshlrev_b32_e32 v20, 16, v22
	v_and_b32_e32 v22, 0xffff0000, v22
	v_pk_mul_f32 v[6:7], v[30:31], v[20:21]
	v_pk_mul_f32 v[20:21], v[32:33], v[22:23]
	v_pk_mul_f32 v[22:23], v[34:35], v[26:27]
	v_mov_b32_e32 v17, v3
	v_or_b32_e32 v16, 0x160, v2
	v_pk_mul_f32 v[26:27], v[36:37], v[28:29]
	v_lshl_add_u64 v[16:17], v[12:13], 0, v[16:17]
	s_waitcnt vmcnt(28)
	v_mul_f32_e32 v4, v124, v6
	v_mul_f32_e32 v6, v125, v20
	v_mul_f32_e32 v8, v126, v22
	v_mul_f32_e32 v9, v127, v26
	v_mul_f32_e32 v4, v4, v7
	v_mul_f32_e32 v6, v6, v21
	v_mul_f32_e32 v7, v8, v23
	v_mul_f32_e32 v8, v9, v27
	v_cvt_pk_bf16_f32 v6, v4, v6
	v_cvt_pk_bf16_f32 v7, v7, v8
	global_store_dwordx2 v[16:17], v[6:7], off
	ds_read2_b64 v[20:23], v109 offset0:48 offset1:52
	v_mov_b32_e32 v17, v3
	v_or_b32_e32 v16, 0x180, v2
	v_lshl_add_u64 v[14:15], v[12:13], 0, v[16:17]
	s_waitcnt lgkmcnt(0)
	v_lshlrev_b32_e32 v30, 16, v21
	v_and_b32_e32 v32, 0xffff0000, v21
	v_lshlrev_b32_e32 v17, 16, v132
	v_and_b32_e32 v21, 0xffff0000, v132
	v_lshlrev_b32_e32 v31, 16, v133
	v_and_b32_e32 v33, 0xffff0000, v133
	v_mul_f32_e32 v4, 0xbfb8aa3b, v17
	v_mul_f32_e32 v19, 0xbfb8aa3b, v21
	v_mul_f32_e32 v24, 0xbfb8aa3b, v31
	v_mul_f32_e32 v25, 0xbfb8aa3b, v33
	v_exp_f32_e32 v4, v4
	v_exp_f32_e32 v19, v19
	v_exp_f32_e32 v24, v24
	v_exp_f32_e32 v25, v25
	v_add_f32_e32 v4, 1.0, v4
	v_add_f32_e32 v19, 1.0, v19
	v_add_f32_e32 v24, 1.0, v24
	v_add_f32_e32 v25, 1.0, v25
	v_rcp_f32_e32 v35, v4
	v_rcp_f32_e32 v37, v19
	v_rcp_f32_e32 v39, v24
	v_rcp_f32_e32 v41, v25
	v_lshlrev_b32_e32 v16, 16, v20
	v_and_b32_e32 v20, 0xffff0000, v20
	v_pk_mul_f32 v[16:17], v[34:35], v[16:17]
	v_pk_mul_f32 v[20:21], v[36:37], v[20:21]
	v_pk_mul_f32 v[24:25], v[38:39], v[30:31]
	v_pk_mul_f32 v[30:31], v[40:41], v[32:33]
	v_mov_b32_e32 v32, v5
	s_waitcnt vmcnt(28)
	v_mul_f32_e32 v4, v134, v16
	v_mul_f32_e32 v8, v135, v20
	v_mul_f32_e32 v9, v136, v24
	v_mul_f32_e32 v10, v137, v30
	v_mul_f32_e32 v8, v8, v21
	v_mul_f32_e32 v9, v9, v25
	v_mul_f32_e32 v4, v4, v17
	v_mul_f32_e32 v10, v10, v31
	v_cvt_pk_bf16_f32 v8, v4, v8
	v_cvt_pk_bf16_f32 v9, v9, v10
	global_store_dwordx2 v[14:15], v[8:9], off
	v_lshlrev_b32_e32 v16, 16, v22
	v_and_b32_e32 v20, 0xffff0000, v22
	v_lshlrev_b32_e32 v22, 16, v23
	v_and_b32_e32 v24, 0xffff0000, v23
	v_lshlrev_b32_e32 v17, 16, v138
	v_and_b32_e32 v21, 0xffff0000, v138
	v_lshlrev_b32_e32 v23, 16, v139
	v_and_b32_e32 v25, 0xffff0000, v139
	v_mul_f32_e32 v4, 0xbfb8aa3b, v17
	v_mul_f32_e32 v19, 0xbfb8aa3b, v21
	v_mul_f32_e32 v26, 0xbfb8aa3b, v23
	v_mul_f32_e32 v27, 0xbfb8aa3b, v25
	v_exp_f32_e32 v4, v4
	v_exp_f32_e32 v19, v19
	v_exp_f32_e32 v26, v26
	v_exp_f32_e32 v27, v27
	v_add_f32_e32 v4, 1.0, v4
	v_add_f32_e32 v19, 1.0, v19
	v_add_f32_e32 v26, 1.0, v26
	v_add_f32_e32 v27, 1.0, v27
	v_rcp_f32_e32 v31, v4
	v_rcp_f32_e32 v33, v19
	v_rcp_f32_e32 v35, v26
	v_rcp_f32_e32 v37, v27
	v_mov_b32_e32 v30, v5
	v_pk_mul_f32 v[16:17], v[30:31], v[16:17]
	v_pk_mul_f32 v[20:21], v[32:33], v[20:21]
	v_pk_mul_f32 v[22:23], v[34:35], v[22:23]
	v_mov_b32_e32 v15, v3
	v_or_b32_e32 v14, 0x1a0, v2
	v_pk_mul_f32 v[24:25], v[36:37], v[24:25]
	v_lshl_add_u64 v[14:15], v[12:13], 0, v[14:15]
	s_waitcnt vmcnt(28)
	v_and_b32_e32 v27, 0xffff0000, v141
	s_waitcnt vmcnt(26)
	v_mul_f32_e32 v4, v144, v16
	v_mul_f32_e32 v8, v145, v20
	v_mul_f32_e32 v9, v146, v22
	v_mul_f32_e32 v10, v147, v24
	v_mul_f32_e32 v8, v8, v21
	v_mul_f32_e32 v9, v9, v23
	v_mul_f32_e32 v4, v4, v17
	v_mul_f32_e32 v10, v10, v25
	v_cvt_pk_bf16_f32 v8, v4, v8
	v_cvt_pk_bf16_f32 v9, v9, v10
	global_store_dwordx2 v[14:15], v[8:9], off
	ds_read2_b64 v[14:17], v109 offset0:56 offset1:60
	v_lshlrev_b32_e32 v23, 16, v140
	v_lshlrev_b32_e32 v25, 16, v141
	v_mul_f32_e32 v4, 0xbfb8aa3b, v23
	v_mul_f32_e32 v29, 0xbfb8aa3b, v27
	s_waitcnt lgkmcnt(0)
	v_lshlrev_b32_e32 v24, 16, v15
	v_and_b32_e32 v26, 0xffff0000, v15
	v_and_b32_e32 v15, 0xffff0000, v140
	v_mul_f32_e32 v19, 0xbfb8aa3b, v15
	v_mul_f32_e32 v28, 0xbfb8aa3b, v25
	v_exp_f32_e32 v4, v4
	v_exp_f32_e32 v19, v19
	v_exp_f32_e32 v28, v28
	v_exp_f32_e32 v29, v29
	v_add_f32_e32 v4, 1.0, v4
	v_add_f32_e32 v19, 1.0, v19
	v_add_f32_e32 v28, 1.0, v28
	v_add_f32_e32 v29, 1.0, v29
	v_rcp_f32_e32 v31, v4
	v_rcp_f32_e32 v33, v19
	v_rcp_f32_e32 v35, v28
	v_rcp_f32_e32 v37, v29
	v_lshlrev_b32_e32 v22, 16, v14
	v_and_b32_e32 v14, 0xffff0000, v14
	v_pk_mul_f32 v[22:23], v[30:31], v[22:23]
	v_pk_mul_f32 v[14:15], v[32:33], v[14:15]
	v_pk_mul_f32 v[24:25], v[34:35], v[24:25]
	v_mov_b32_e32 v21, v3
	v_or_b32_e32 v20, 0x1c0, v2
	v_pk_mul_f32 v[26:27], v[36:37], v[26:27]
	v_lshl_add_u64 v[20:21], v[12:13], 0, v[20:21]
	v_or_b32_e32 v2, 0x1e0, v2
	v_mov_b32_e32 v28, v5
	v_lshlrev_b32_e32 v19, 16, v143
	v_lshl_add_u64 v[12:13], v[12:13], 0, v[2:3]
	v_mov_b32_e32 v30, v0
	s_waitcnt vmcnt(26)
	v_mul_f32_e32 v4, v148, v22
	v_mul_f32_e32 v8, v149, v14
	v_mul_f32_e32 v9, v150, v24
	v_mul_f32_e32 v10, v151, v26
	v_mul_f32_e32 v8, v8, v15
	v_mul_f32_e32 v9, v9, v25
	v_mul_f32_e32 v4, v4, v23
	v_mul_f32_e32 v10, v10, v27
	v_cvt_pk_bf16_f32 v8, v4, v8
	v_cvt_pk_bf16_f32 v9, v9, v10
	global_store_dwordx2 v[20:21], v[8:9], off
	v_lshlrev_b32_e32 v18, 16, v17
	v_and_b32_e32 v20, 0xffff0000, v17
	v_mov_b32_e32 v22, v5
	v_mov_b32_e32 v24, v5
	v_mov_b32_e32 v26, v5
	v_lshlrev_b32_e32 v5, 16, v142
	v_and_b32_e32 v17, 0xffff0000, v142
	v_and_b32_e32 v21, 0xffff0000, v143
	v_mul_f32_e32 v2, 0xbfb8aa3b, v5
	v_mul_f32_e32 v6, 0xbfb8aa3b, v17
	v_mul_f32_e32 v7, 0xbfb8aa3b, v19
	v_mul_f32_e32 v23, 0xbfb8aa3b, v21
	v_exp_f32_e32 v2, v2
	v_exp_f32_e32 v6, v6
	v_exp_f32_e32 v7, v7
	v_exp_f32_e32 v23, v23
	v_add_f32_e32 v2, 1.0, v2
	v_add_f32_e32 v6, 1.0, v6
	v_add_f32_e32 v7, 1.0, v7
	v_add_f32_e32 v29, 1.0, v23
	v_rcp_f32_e32 v23, v2
	v_rcp_f32_e32 v25, v6
	v_rcp_f32_e32 v27, v7
	v_rcp_f32_e32 v29, v29
	v_lshlrev_b32_e32 v4, 16, v16
	v_and_b32_e32 v16, 0xffff0000, v16
	v_pk_mul_f32 v[4:5], v[22:23], v[4:5]
	v_pk_mul_f32 v[6:7], v[24:25], v[16:17]
	v_pk_mul_f32 v[16:17], v[26:27], v[18:19]
	v_pk_mul_f32 v[18:19], v[28:29], v[20:21]
	v_mov_b64_e32 v[14:15], s[88:89]
	s_waitcnt vmcnt(26)
	v_mul_f32_e32 v2, v152, v4
	v_mul_f32_e32 v4, v153, v6
	v_mul_f32_e32 v6, v154, v16
	v_mul_f32_e32 v8, v155, v18
	v_mul_f32_e32 v2, v2, v5
	v_mul_f32_e32 v4, v4, v7
	v_mul_f32_e32 v5, v6, v17
	v_mul_f32_e32 v6, v8, v19
	v_cvt_pk_bf16_f32 v4, v2, v4
	v_cvt_pk_bf16_f32 v5, v5, v6
	global_store_dwordx2 v[12:13], v[4:5], off
	s_nop 0
	v_and_b32_e32 v52, 15, v30
	v_ashrrev_i32_e32 v2, 6, v30
	v_or_b32_e32 v5, s20, v52
	v_ashrrev_i32_e32 v46, 1, v30
	v_lshl_add_u32 v116, v2, 4, v5
	v_lshl_add_u32 v4, s0, 8, v46
	v_mad_i64_i32 v[118:119], s[0:1], v116, s92, v[14:15]
	v_ashrrev_i32_e32 v5, 31, v4
	v_readlane_b32 s0, v244, 50
	v_and_b32_e32 v50, 1, v30
	v_lshlrev_b64 v[4:5], 10, v[4:5]
	v_readlane_b32 s1, v244, 51
	v_bfe_u32 v47, v30, 4, 2
	v_lshlrev_b32_e32 v44, 6, v50
	v_lshl_add_u64 v[4:5], s[0:1], 0, v[4:5]
	v_lshlrev_b32_e32 v114, 4, v47
	v_lshl_add_u64 v[20:21], v[4:5], 0, v[44:45]
	v_lshl_add_u64 v[120:121], v[118:119], 0, v[114:115]
	s_waitcnt vmcnt(16)
	v_and_b32_e32 v108, 63, v0
	v_lshlrev_b32_e32 v108, 2, v108
	v_add_u32_e32 v108, 0x21c00, v108
	ds_write_b32 v108, v195
	s_waitcnt lgkmcnt(0)
	v_mov_b64_e32 v[4:5], v[156:157]
	v_mov_b64_e32 v[6:7], v[158:159]
	v_mov_b64_e32 v[12:13], v[160:161]
	v_mov_b64_e32 v[14:15], v[162:163]
	v_mov_b64_e32 v[16:17], v[164:165]
	v_mov_b64_e32 v[18:19], v[166:167]
	v_mov_b64_e32 v[8:9], v[172:173]
	v_mov_b64_e32 v[10:11], v[174:175]
	v_mov_b64_e32 v[28:29], v[176:177]
	v_mov_b64_e32 v[30:31], v[178:179]
	v_mov_b64_e32 v[32:33], v[196:197]
	v_mov_b64_e32 v[34:35], v[198:199]
	v_mov_b64_e32 v[36:37], v[200:201]
	v_mov_b64_e32 v[38:39], v[202:203]
	v_mov_b64_e32 v[40:41], v[204:205]
	v_mov_b64_e32 v[42:43], v[206:207]
	s_nop 0
	v_mov_b64_e32 v[20:21], v[208:209]
	v_mov_b64_e32 v[22:23], v[210:211]
	v_mov_b64_e32 v[24:25], v[212:213]
	v_mov_b64_e32 v[26:27], v[214:215]
	v_readlane_b32 s0, v243, 0
	v_mul_lo_u32 v45, v46, s97
	s_and_b32 s0, s0, 7
	v_add_u32_e32 v48, 0, v45
	s_lshl_b32 s2, s0, 18
	v_add_u32_e32 v132, v48, v44
	v_mad_u64_u32 v[48:49], s[0:1], v46, s98, v[48:49]
	v_mul_u32_u24_e32 v45, 0x4200, v50
	v_lshlrev_b32_e32 v50, 7, v50
	v_mul_lo_u32 v131, v2, s93
	v_lshlrev_b32_e32 v2, 3, v47
	v_add_u32_e32 v122, 0x21c00, v50
	v_lshlrev_b32_e32 v50, 5, v47
	v_or_b32_e32 v47, 16, v52
	s_movk_i32 s0, 0x210
	v_lshl_add_u64 v[124:125], s[8:9], 0, v[50:51]
	global_load_dwordx4 v[224:227], v[124:125], off
	global_load_dwordx4 v[228:231], v[124:125], off offset:128
	global_load_dwordx4 v[232:235], v[124:125], off offset:16
	global_load_dwordx4 v[236:239], v[124:125], off offset:144
	v_mul_u32_u24_e32 v51, 0x210, v47
	v_mad_u32_u24 v47, v52, s0, v131
	v_add3_u32 v134, v47, v2, s96
	v_ashrrev_i32_e32 v47, 31, v46
	v_lshlrev_b64 v[46:47], 10, v[46:47]
	v_add_u32_e32 v49, 0, v114
	s_mov_b32 s1, s3
	v_lshl_add_u64 v[46:47], s[2:3], 0, v[46:47]
	v_mov_b32_e32 v133, v49
	v_mul_u32_u24_e32 v50, 0x90, v52
	v_writelane_b32 v244, s0, 62
	v_or_b32_e32 v46, v46, v44
	v_mul_u32_u24_e32 v115, 0x210, v52
	v_ashrrev_i32_e32 v117, 31, v116
	v_writelane_b32 v244, s1, 63
	v_lshl_add_u64 v[126:127], s[6:7], 0, v[46:47]
	s_mov_b64 s[0:1], 64
	v_and_b32_e32 v241, 24, v48
	v_and_b32_e32 v242, 32, v48
	v_and_b32_e32 v48, 0xffffffc7, v48
	v_lshlrev_b32_e32 v241, 1, v241
	v_lshrrev_b32_e32 v242, 2, v242
	v_or3_b32 v48, v48, v241, v242
	v_add_u32_e32 v135, v48, v45
	v_add_u32_e32 v136, v49, v50
	v_add_u32_e32 v137, v133, v51
	v_add_u32_e32 v240, v133, v115
	v_add_u32_e32 v240, 0x9000, v240
	v_add_u32_e32 v241, 0x9000, v137
	v_add_u32_e32 v242, 0xb000, v137
	v_add_u32_e32 v245, 0xd000, v137
	s_branch .LBB0_210
